# MLA loop: softmax row-sum with packed f32 adds (18 instead of 32 VALU ops per tile step)
# baseline (speedup 1.0000x reference)
.Lmla_norescale:
	s_add_i32 s10, s1, -1
	s_and_b32 s11, s10, 1
	s_mul_i32 s7, s11, 0x3400
	v_add_u32_e32 v147, s7, v149
	ds_read_b128 v[110:113], v147
	ds_read_b128 v[114:117], v147 offset:32
	ds_read_b128 v[118:121], v147 offset:64
	ds_read_b128 v[152:155], v147 offset:96
	s_and_b32 s6, s1, 1
	v_exp_f32_e32 v141, v48
	v_exp_f32_e32 v157, v49
	v_exp_f32_e32 v158, v50
	v_exp_f32_e32 v159, v51
	v_exp_f32_e32 v160, v52
	v_exp_f32_e32 v161, v53
	v_exp_f32_e32 v162, v54
	v_exp_f32_e32 v163, v55
	v_exp_f32_e32 v164, v56
	v_exp_f32_e32 v165, v57
	v_exp_f32_e32 v166, v58
	v_exp_f32_e32 v167, v59
	v_exp_f32_e32 v168, v60
	v_exp_f32_e32 v169, v61
	v_exp_f32_e32 v170, v62
	v_exp_f32_e32 v171, v63
	s_waitcnt lgkmcnt(3)
	v_mfma_f32_32x32x16_bf16 v[48:63], v[110:113], v[106:109], v[64:79]
	ds_read_b128 v[234:237], v147 offset:128
	v_exp_f32_e32 v172, v32
	v_exp_f32_e32 v173, v33
	v_exp_f32_e32 v174, v34
	s_waitcnt lgkmcnt(3)
	v_mfma_f32_32x32x16_bf16 v[48:63], v[114:117], v[102:105], v[48:63]
	ds_read_b128 v[212:215], v147 offset:160
	v_exp_f32_e32 v175, v35
	v_exp_f32_e32 v176, v36
	v_exp_f32_e32 v177, v37
	s_waitcnt lgkmcnt(3)
	v_mfma_f32_32x32x16_bf16 v[48:63], v[118:121], v[92:95], v[48:63]
	ds_read_b128 v[216:219], v147 offset:6656
	v_exp_f32_e32 v178, v38
	v_exp_f32_e32 v179, v39
	v_exp_f32_e32 v187, v40
	s_waitcnt lgkmcnt(3)
	v_mfma_f32_32x32x16_bf16 v[48:63], v[152:155], v[88:91], v[48:63]
	ds_read_b128 v[238:241], v147 offset:6688
	v_exp_f32_e32 v188, v41
	v_exp_f32_e32 v189, v42
	v_exp_f32_e32 v190, v43
	s_waitcnt lgkmcnt(3)
	v_mfma_f32_32x32x16_bf16 v[48:63], v[234:237], v[84:87], v[48:63]
	ds_read_b128 v[242:245], v147 offset:6720
	v_exp_f32_e32 v191, v44
	v_exp_f32_e32 v192, v45
	v_exp_f32_e32 v193, v46
	s_waitcnt lgkmcnt(3)
	v_mfma_f32_32x32x16_bf16 v[48:63], v[212:215], v[80:83], v[48:63]
	ds_read_b128 v[246:249], v147 offset:6752
	v_exp_f32_e32 v194, v47
	v_cvt_pk_bf16_f32 v196, v141, v157
	v_cvt_pk_bf16_f32 v197, v158, v159
	s_waitcnt lgkmcnt(3)
	v_mfma_f32_32x32x16_bf16 v[32:47], v[216:219], v[106:109], v[64:79]
	ds_read_b128 v[110:113], v147 offset:6784
	v_cvt_pk_bf16_f32 v198, v160, v161
	v_cvt_pk_bf16_f32 v199, v162, v163
	v_cvt_pk_bf16_f32 v200, v164, v165
	v_cvt_pk_bf16_f32 v201, v166, v167
	s_waitcnt lgkmcnt(3)
	v_mfma_f32_32x32x16_bf16 v[32:47], v[238:241], v[102:105], v[32:47]
	ds_read_b128 v[114:117], v147 offset:6816
	v_cvt_pk_bf16_f32 v202, v168, v169
	v_cvt_pk_bf16_f32 v203, v170, v171
	v_cvt_pk_bf16_f32 v204, v172, v173
	v_cvt_pk_bf16_f32 v205, v174, v175
	s_waitcnt lgkmcnt(3)
	v_mfma_f32_32x32x16_bf16 v[32:47], v[242:245], v[92:95], v[32:47]
	s_mul_i32 s7, s6, 0x2400
	v_add_u32_e32 v156, s7, v97
	ds_read_b64_tr_b16 v[118:119], v156 offset:26624
	ds_read_b64_tr_b16 v[120:121], v156 offset:27776
	ds_read_b64_tr_b16 v[154:155], v156 offset:27840
	ds_read_b64_tr_b16 v[152:153], v156 offset:26688
	v_cvt_pk_bf16_f32 v206, v176, v177
	v_cvt_pk_bf16_f32 v207, v178, v179
	v_cvt_pk_bf16_f32 v208, v187, v188
	s_waitcnt lgkmcnt(6)
	v_mfma_f32_32x32x16_bf16 v[32:47], v[246:249], v[88:91], v[32:47]
	ds_read_b64_tr_b16 v[234:235], v156 offset:28928
	ds_read_b64_tr_b16 v[236:237], v156 offset:30080
	ds_read_b64_tr_b16 v[214:215], v156 offset:30144
	ds_read_b64_tr_b16 v[212:213], v156 offset:28992
	v_cvt_pk_bf16_f32 v209, v189, v190
	v_cvt_pk_bf16_f32 v210, v191, v192
	v_cvt_pk_bf16_f32 v211, v193, v194
	v_add_f32_e32 v101, v157, v141
	s_waitcnt lgkmcnt(9)
	v_mfma_f32_32x32x16_bf16 v[32:47], v[110:113], v[84:87], v[32:47]
	ds_read_b64_tr_b16 v[216:217], v156 offset:31232
	ds_read_b64_tr_b16 v[218:219], v156 offset:32384
	ds_read_b64_tr_b16 v[240:241], v156 offset:32448
	ds_read_b64_tr_b16 v[238:239], v156 offset:31296
	v_pk_add_f32 v[172:173], v[172:173], v[158:159]
	v_pk_add_f32 v[172:173], v[172:173], v[160:161]
	v_pk_add_f32 v[172:173], v[172:173], v[162:163]
	v_pk_add_f32 v[172:173], v[172:173], v[164:165]
	s_waitcnt lgkmcnt(12)
	v_mfma_f32_32x32x16_bf16 v[32:47], v[114:117], v[80:83], v[32:47]
	ds_read_b64_tr_b16 v[242:243], v156 offset:33536
	ds_read_b64_tr_b16 v[244:245], v156 offset:34688
	ds_read_b64_tr_b16 v[248:249], v156 offset:34752
	ds_read_b64_tr_b16 v[246:247], v156 offset:33600
	v_pk_add_f32 v[172:173], v[172:173], v[166:167]
	v_pk_add_f32 v[172:173], v[172:173], v[168:169]
	v_pk_add_f32 v[172:173], v[172:173], v[170:171]
	s_nop 1
	v_pk_add_f32 v[172:173], v[172:173], v[174:175]
	v_pk_add_f32 v[172:173], v[172:173], v[176:177]
	v_pk_add_f32 v[172:173], v[172:173], v[178:179]
	v_pk_add_f32 v[172:173], v[172:173], v[188:189]
	s_waitcnt lgkmcnt(14)
	v_mfma_f32_32x32x16_bf16 v[16:31], v[118:121], v[196:199], v[16:31]
	v_pk_add_f32 v[172:173], v[172:173], v[190:191]
	v_pk_add_f32 v[172:173], v[172:173], v[192:193]
	v_add_f32_e32 v195, v187, v194
	v_max3_f32 v100, v48, v49, v50
	v_max3_f32 v100, v100, v51, v52
	v_max3_f32 v100, v100, v53, v54
	s_waitcnt lgkmcnt(12)
	v_mfma_f32_32x32x16_bf16 v[0:15], v[152:155], v[196:199], v[0:15]
	s_mulk_i32 s6, 0x3400
	s_add_i32 s12, s6, 0
	v_add3_u32 v156, s12, v150, v134
	s_waitcnt vmcnt(1)
	ds_write_b128 v156, v[130:133]
	s_and_saveexec_b64 s[6:7], s[38:39]
	v_add3_u32 v156, s12, v151, v136
	ds_write_b128 v156, v[122:125] offset:128
	s_or_b64 exec, exec, s[6:7]
	v_add_f32_e32 v195, v195, v101
	v_add_f32_e32 v101, v172, v173
	v_max3_f32 v100, v100, v55, v56
	v_max3_f32 v100, v100, v57, v58
	s_waitcnt lgkmcnt(11)
	v_mfma_f32_32x32x16_bf16 v[16:31], v[234:237], v[200:203], v[16:31]
	v_add_f32_e32 v195, v195, v101
	v_max3_f32 v100, v100, v59, v60
	v_max3_f32 v100, v100, v61, v62
	v_max3_f32 v100, v100, v63, v63
	s_waitcnt lgkmcnt(9)
	v_mfma_f32_32x32x16_bf16 v[0:15], v[212:215], v[200:203], v[0:15]
	s_mulk_i32 s11, 0x2400
	v_add_u32_e32 v156, s11, v135
	v_add_u32_e32 v228, 64, v140
	s_waitcnt vmcnt(0)
	ds_write_b128 v156, v[126:129] offset:26624
	s_waitcnt lgkmcnt(8)
	v_mfma_f32_32x32x16_bf16 v[16:31], v[216:219], v[204:207], v[16:31]
	v_max3_f32 v98, v32, v33, v34
	v_max3_f32 v98, v98, v35, v36
	v_max3_f32 v98, v98, v37, v38
	s_waitcnt lgkmcnt(6)
	v_mfma_f32_32x32x16_bf16 v[0:15], v[238:241], v[204:207], v[0:15]
	s_cmpk_lt_u32 s10, 0x42
	s_cbranch_scc0 .Lmla_noload
	v_ashrrev_i32_e32 v229, 31, v228
	v_lshlrev_b64 v[220:221], 10, v[228:229]
	v_lshl_add_u64 v[220:221], v[142:143], 0, v[220:221]
	global_load_dwordx4 v[130:133], v[220:221], off
	s_and_saveexec_b64 s[6:7], s[38:39]
	s_cbranch_execz .Lmla_norr
	v_ashrrev_i32_e32 v147, 31, v146
	v_lshlrev_b64 v[220:221], 6, v[146:147]
	v_lshl_add_u64 v[220:221], v[144:145], 0, v[220:221]
	global_load_dwordx4 v[122:125], v[220:221], off

.Lmla_noload:
	v_ashrrev_i32_e32 v141, 31, v140
	v_lshlrev_b64 v[220:221], 10, v[140:141]
	v_lshl_add_u64 v[220:221], v[142:143], 0, v[220:221]
	global_load_dwordx4 v[126:129], v[220:221], off offset:128
	s_waitcnt lgkmcnt(4)
	v_mfma_f32_32x32x16_bf16 v[16:31], v[242:245], v[208:211], v[16:31]
	v_max3_f32 v98, v98, v39, v40
	v_max3_f32 v98, v98, v41, v42
	v_max3_f32 v98, v98, v43, v44
	s_waitcnt lgkmcnt(2)
	v_mfma_f32_32x32x16_bf16 v[0:15], v[246:249], v[208:211], v[0:15]
	v_max3_f32 v98, v98, v45, v46
	v_max3_f32 v98, v98, v47, v47
	v_max3_f32 v100, v100, v98, v98
	ds_bpermute_b32 v98, v137, v100
	v_add_f32_e32 v138, v138, v195
	s_waitcnt lgkmcnt(0)
	v_max3_f32 v100, v100, v98, v100
	s_barrier
	s_add_i32 s1, s1, 1
	v_add_u32_e32 v146, 64, v146
	s_cmpk_eq_i32 s1, 0x44
	s_cbranch_scc1 .LBB0_559
	v_mov_b32_e32 v140, v228
	s_branch .LBB0_546
